# first final-attention item: barrier-5 wait and merge-operand loads moved two key tiles later
# baseline (speedup 1.0000x reference)
.LBB0_851:
	s_cmp_ge_i32 s91, s9
	s_cselect_b64 s[76:77], -1, 0
	s_cmp_lt_i32 s91, s9
	s_cbranch_scc1 .LBB0_853
	s_waitcnt lgkmcnt(3)
	v_mfma_f32_32x32x16_bf16 v[18:33], v[12:15], v[94:97], 0
	v_add_u32_e32 v2, s86, v204
	ds_read_b64_tr_b16 v[146:147], v2 offset:4096
	ds_read_b64_tr_b16 v[148:149], v2 offset:5120
	ds_read_b64_tr_b16 v[150:151], v2 offset:6144
	ds_read_b64_tr_b16 v[152:153], v2 offset:7168
	v_add_u32_e32 v2, s86, v205
	ds_read_b64_tr_b16 v[158:159], v2 offset:4096
	ds_read_b64_tr_b16 v[160:161], v2 offset:5120
	ds_read_b64_tr_b16 v[154:155], v2 offset:6144
	ds_read_b64_tr_b16 v[156:157], v2 offset:7168
	s_waitcnt lgkmcnt(10)
	v_mfma_f32_32x32x16_bf16 v[18:33], v[8:11], v[90:93], v[18:33]
	s_waitcnt lgkmcnt(9)
	v_mfma_f32_32x32x16_bf16 v[18:33], v[66:69], v[86:89], v[18:33]
	s_waitcnt lgkmcnt(8)
	v_mfma_f32_32x32x16_bf16 v[18:33], v[4:7], v[82:85], v[18:33]
.LBB0_853:
	s_cmp_lg_u32 s6, 0
	s_cbranch_scc1 .Lb5mid_go
	s_mov_b64 s[98:99], exec
	v_readlane_b32 s100, v254, 6
	v_readlane_b32 s101, v254, 7
	s_and_b64 s[100:101], s[98:99], s[100:101]
	s_mov_b64 exec, s[100:101]
	s_cbranch_execz .Lsplit5_join
	v_mov_b32_e32 v240, 0x7000
	s_mov_b32 s100, 0

.Lsplit5_join:
	s_mov_b64 exec, s[98:99]
	s_barrier
	s_and_b32 s98, s84, 0x3fffffc0
	s_lshl_b32 s98, s98, 1
	s_mov_b32 s99, 0
	v_lshl_or_b32 v234, s74, 2, v198
	v_mov_b32_e32 v235, 0
	v_ashrrev_i32_e32 v240, 2, v192
	v_lshl_add_u64 v[236:237], v[184:185], 0, s[98:99]
	v_lshlrev_b64 v[238:239], 12, v[234:235]
	v_ashrrev_i32_e32 v241, 31, v240
	v_or_b32_e32 v234, s85, v196
	s_ashr_i32 s98, s7, 4
	v_lshl_add_u64 v[240:241], v[238:239], 0, v[240:241]
	v_lshlrev_b64 v[242:243], 10, v[234:235]
	s_ashr_i32 s99, s98, 31
	v_lshl_add_u64 v[244:245], v[242:243], 0, s[98:99]
	v_lshlrev_b64 v[246:247], 7, v[240:241]
	v_lshl_add_u64 v[246:247], v[180:181], 0, v[246:247]
	v_lshlrev_b64 v[248:249], 7, v[244:245]
	v_ashrrev_i32_e32 v193, 31, v192
	v_lshl_add_u64 v[248:249], v[182:183], 0, v[248:249]
	global_load_dwordx4 v[142:145], v[246:247], off
	global_load_dwordx4 v[138:141], v[248:249], off
	v_lshlrev_b64 v[246:247], 10, v[192:193]
	v_lshl_add_u64 v[244:245], v[244:245], 2, s[0:1]
	v_lshl_add_u64 v[246:247], v[236:237], 0, v[246:247]
	v_lshl_add_u64 v[240:241], v[240:241], 2, s[0:1]
	v_add_co_u32_e32 v244, vcc, s4, v244
	s_nop 0
	v_addc_co_u32_e32 v245, vcc, 0, v245, vcc
	global_load_dwordx4 v[134:137], v[246:247], off
	global_load_dword v230, v[240:241], off
	global_load_dword v231, v[244:245], off
	v_or_b32_e32 v240, 8, v192
	v_ashrrev_i32_e32 v244, 2, v240
	v_and_or_b32 v234, v240, 15, s85
	v_ashrrev_i32_e32 v245, 31, v244
	v_lshlrev_b64 v[246:247], 10, v[234:235]
	v_lshl_add_u64 v[244:245], v[238:239], 0, v[244:245]
	v_lshl_add_u64 v[246:247], v[246:247], 0, s[98:99]
	v_ashrrev_i32_e32 v241, 31, v240
	v_lshlrev_b64 v[248:249], 7, v[244:245]
	v_lshlrev_b64 v[250:251], 7, v[246:247]
	v_lshlrev_b64 v[240:241], 10, v[240:241]
	v_lshl_add_u64 v[246:247], v[246:247], 2, s[0:1]
	v_lshl_add_u64 v[248:249], v[180:181], 0, v[248:249]
	v_lshl_add_u64 v[240:241], v[236:237], 0, v[240:241]
	v_add_co_u32_e32 v246, vcc, s4, v246
	v_lshl_add_u64 v[250:251], v[182:183], 0, v[250:251]
	global_load_dwordx4 v[130:133], v[248:249], off
	global_load_dwordx4 v[126:129], v[250:251], off
	v_lshl_add_u64 v[244:245], v[244:245], 2, s[0:1]
	v_addc_co_u32_e32 v247, vcc, 0, v247, vcc
	global_load_dwordx4 v[122:125], v[240:241], off
	global_load_dword v228, v[244:245], off
	global_load_dword v229, v[246:247], off
	v_or_b32_e32 v240, 16, v192
	v_ashrrev_i32_e32 v244, 2, v240
	v_ashrrev_i32_e32 v246, 4, v240
	v_ashrrev_i32_e32 v245, 31, v244
	v_ashrrev_i32_e32 v247, 31, v246
	v_lshl_add_u64 v[244:245], v[238:239], 0, v[244:245]
	v_lshl_add_u64 v[242:243], v[242:243], 0, v[246:247]
	v_ashrrev_i32_e32 v241, 31, v240
	v_lshlrev_b64 v[246:247], 7, v[244:245]
	v_lshlrev_b64 v[248:249], 7, v[242:243]
	v_lshlrev_b64 v[240:241], 10, v[240:241]
	v_lshl_add_u64 v[242:243], v[242:243], 2, s[0:1]
	v_lshl_add_u64 v[246:247], v[180:181], 0, v[246:247]
	v_lshl_add_u64 v[240:241], v[236:237], 0, v[240:241]
	v_add_co_u32_e32 v242, vcc, s4, v242
	v_lshl_add_u64 v[248:249], v[182:183], 0, v[248:249]
	global_load_dwordx4 v[118:121], v[246:247], off
	global_load_dwordx4 v[114:117], v[248:249], off
	v_lshl_add_u64 v[244:245], v[244:245], 2, s[0:1]
	v_addc_co_u32_e32 v243, vcc, 0, v243, vcc
	global_load_dwordx4 v[110:113], v[240:241], off
	global_load_dword v226, v[244:245], off
	global_load_dword v227, v[242:243], off
	v_or_b32_e32 v240, 24, v192
	v_ashrrev_i32_e32 v242, 2, v240
	v_ashrrev_i32_e32 v243, 31, v242
	v_and_or_b32 v234, v240, 15, s85
	v_ashrrev_i32_e32 v244, 4, v240
	v_lshl_add_u64 v[238:239], v[238:239], 0, v[242:243]
	v_lshlrev_b64 v[242:243], 10, v[234:235]
	v_ashrrev_i32_e32 v245, 31, v244
	v_ashrrev_i32_e32 v241, 31, v240
	v_lshl_add_u64 v[242:243], v[242:243], 0, v[244:245]
	v_lshlrev_b64 v[240:241], 10, v[240:241]
	v_lshlrev_b64 v[244:245], 7, v[238:239]
	v_lshl_add_u64 v[236:237], v[236:237], 0, v[240:241]
	v_lshl_add_u64 v[240:241], v[242:243], 2, s[0:1]
	v_lshl_add_u64 v[244:245], v[180:181], 0, v[244:245]
	v_lshlrev_b64 v[246:247], 7, v[242:243]
	v_add_co_u32_e32 v240, vcc, 0x80000, v240
	v_lshl_add_u64 v[246:247], v[182:183], 0, v[246:247]
	global_load_dwordx4 v[106:109], v[244:245], off
	global_load_dwordx4 v[102:105], v[246:247], off
	v_lshl_add_u64 v[238:239], v[238:239], 2, s[0:1]
	v_addc_co_u32_e32 v241, vcc, 0, v241, vcc
	global_load_dwordx4 v[98:101], v[236:237], off
	global_load_dword v224, v[238:239], off
	global_load_dword v225, v[240:241], off
.Lb5mid_go:
	v_add_u32_e32 v2, v212, v200
	s_waitcnt lgkmcnt(0)
	v_add_u32_e32 v4, v212, v201
	ds_read_b128 v[12:15], v2 offset:8192
	ds_read_b128 v[8:11], v4 offset:8192
	v_add_u32_e32 v2, v212, v202
	v_add_u32_e32 v4, v212, v203
	ds_read_b128 v[66:69], v2 offset:8192
	ds_read_b128 v[4:7], v4 offset:8192
	s_andn2_b64 vcc, exec, s[76:77]
	s_cbranch_vccnz .LBB0_857
	s_nop 0
	v_max_f32_e32 v2, v19, v19
	v_max_f32_e32 v16, v18, v18
	v_max_f32_e32 v2, v16, v2
	v_max3_f32 v2, v2, v20, v21
	v_max3_f32 v2, v2, v22, v23
	v_mbcnt_hi_u32_b32 v16, -1, v1
	v_max3_f32 v2, v2, v24, v25
	v_and_b32_e32 v70, 64, v16
	v_max3_f32 v2, v2, v26, v27
	v_xor_b32_e32 v17, 32, v16
	v_add_u32_e32 v70, 64, v70
	v_max3_f32 v2, v2, v28, v29
	v_cmp_lt_i32_e32 vcc, v17, v70
	v_max3_f32 v2, v2, v30, v31
	v_max3_f32 v2, v2, v32, v33
	v_cndmask_b32_e32 v16, v16, v17, vcc
	v_lshlrev_b32_e32 v16, 2, v16
	ds_bpermute_b32 v16, v16, v2
	s_waitcnt lgkmcnt(0)
	v_max_f32_e32 v16, v16, v16
	v_max_f32_e32 v2, v2, v16
	v_mul_f32_e32 v2, 0x3fb8aa3b, v2
	v_add_f32_e32 v16, 0x41380000, v233
	v_cmp_gt_f32_e32 vcc, v2, v16
	s_cbranch_vccz .LBB0_856
	v_max_f32_e32 v2, v2, v2
	v_max_f32_e32 v16, v233, v233
	v_max_f32_e32 v16, v16, v2
	v_sub_f32_e32 v2, v233, v16
	v_exp_f32_e32 v2, v2
	v_mov_b32_e32 v233, v16
	v_pk_mul_f32 v[48:49], v[48:49], v[2:3] op_sel_hi:[1,0]
	v_pk_mul_f32 v[46:47], v[46:47], v[2:3] op_sel_hi:[1,0]
	v_pk_mul_f32 v[44:45], v[44:45], v[2:3] op_sel_hi:[1,0]
	v_pk_mul_f32 v[42:43], v[42:43], v[2:3] op_sel_hi:[1,0]
	v_pk_mul_f32 v[40:41], v[40:41], v[2:3] op_sel_hi:[1,0]
	v_pk_mul_f32 v[38:39], v[38:39], v[2:3] op_sel_hi:[1,0]
	v_pk_mul_f32 v[36:37], v[36:37], v[2:3] op_sel_hi:[1,0]
	v_pk_mul_f32 v[34:35], v[34:35], v[2:3] op_sel_hi:[1,0]
	v_pk_mul_f32 v[64:65], v[64:65], v[2:3] op_sel_hi:[1,0]
	v_pk_mul_f32 v[62:63], v[62:63], v[2:3] op_sel_hi:[1,0]
	v_pk_mul_f32 v[60:61], v[60:61], v[2:3] op_sel_hi:[1,0]
	v_pk_mul_f32 v[58:59], v[58:59], v[2:3] op_sel_hi:[1,0]
	v_pk_mul_f32 v[56:57], v[56:57], v[2:3] op_sel_hi:[1,0]
	v_pk_mul_f32 v[54:55], v[54:55], v[2:3] op_sel_hi:[1,0]
	v_pk_mul_f32 v[52:53], v[52:53], v[2:3] op_sel_hi:[1,0]
	v_pk_mul_f32 v[50:51], v[50:51], v[2:3] op_sel_hi:[1,0]
	v_mul_f32_e32 v232, v232, v2
